# v093 + Y-store block de-serialised: both LDS read pairs issued together, first pair consumed under lgkmcnt(2)
# speedup vs baseline: 1.0038x; 1.0033x over previous
; #define LAS __attribute__((address_space(3)))
; DI void phase_rglru(const Params& p, unsigned char* shm) {
;     ...
;             __syncthreads();
;             const size_t ob = base + (size_t)tile * 64 * 1536;
; #pragma unroll
;             for (int j = 0; j < 3; ++j) *(u32x4*)(Y + ob + goff[j]) = *(const LAS u32x4*)(lds + GT + loff[j]);
.LBB0_842:
	s_or_b64 exec, exec, s[2:3]
	s_waitcnt lgkmcnt(0)
	s_barrier
	s_lshl_b64 s[2:3], s[10:11], 1
	s_add_u32 s2, s62, s2
	s_addc_u32 s3, s63, s3
	v_mov_b32_e32 v132, 0x5040100
	v_mov_b32_e32 v133, 0x7060302
	v_mul_hi_i32 v120, v192, s71
	v_ashrrev_i32_e32 v120, 2, v120
	v_mul_u32_u24_e32 v121, 24, v120
	v_sub_u32_e32 v121, v192, v121
	v_mul_u32_u24_e32 v122, 0x320, v120
	v_lshl_add_u32 v122, v121, 5, v122
	v_mul_u32_u24_e32 v123, 0x1800, v120
	v_lshl_add_u32 v123, v121, 4, v123
	ds_read_b128 v[124:127], v122 offset:26880
	ds_read_b128 v[128:131], v122 offset:26896
	v_add_u32_e32 v134, 0x200, v192
	v_cmp_gt_u32_e32 vcc, 0x100, v192
	v_mul_hi_i32 v135, v134, s71
	v_ashrrev_i32_e32 v135, 2, v135
	v_mul_u32_u24_e32 v136, 24, v135
	v_sub_u32_e32 v136, v134, v136
	v_mul_u32_u24_e32 v137, 0x320, v135
	v_lshl_add_u32 v137, v136, 5, v137
	v_mul_u32_u24_e32 v138, 0x1800, v135
	v_lshl_add_u32 v138, v136, 4, v138
	s_add_i32 s64, s64, 1
	ds_read_b128 v[148:151], v137 offset:26880
	ds_read_b128 v[210:213], v137 offset:26896
	s_waitcnt lgkmcnt(2)
	v_perm_b32 v140, v125, v124, v132
	v_perm_b32 v141, v127, v126, v132
	v_perm_b32 v142, v129, v128, v132
	v_perm_b32 v143, v131, v130, v132
	v_perm_b32 v144, v125, v124, v133
	v_perm_b32 v145, v127, v126, v133
	v_perm_b32 v146, v129, v128, v133
	v_perm_b32 v147, v131, v130, v133
	global_store_dwordx4 v123, v[140:143], s[2:3]
	global_store_dwordx4 v123, v[144:147], s[2:3] offset:3072
	s_cbranch_vccz .Lys_done
	s_waitcnt lgkmcnt(0)
	v_perm_b32 v140, v149, v148, v132
	v_perm_b32 v141, v151, v150, v132
	v_perm_b32 v142, v211, v210, v132
	v_perm_b32 v143, v213, v212, v132
	v_perm_b32 v144, v149, v148, v133
	v_perm_b32 v145, v151, v150, v133
	v_perm_b32 v146, v211, v210, v133
	v_perm_b32 v147, v213, v212, v133
	global_store_dwordx4 v138, v[140:143], s[2:3]
	global_store_dwordx4 v138, v[144:147], s[2:3] offset:3072
